# w_in phase: GELU (round-0, even-XCD) units moved from the three-unit workgroups 0..127 to the two-unit workgroups 128..255 by exchanging L in [0,128) with [384,512)
# speedup vs baseline: 1.0035x; 1.0035x over previous
;     __device__ __forceinline__ bool next(int i, pg8::Unit& u) const {
;         const int L = i * G + c;
;         if (kind == 0) {
;             if (L < 512) { int pm, pn; order(L, 512, 32, 16, pm, pn);
;                 u.A = A0 + (size_t)pm * 256 * DM * 2; u.B = B0 + (size_t)pn * 256 * DM * 2; u.O = O0 + ((size_t)pm * 256 * ZW + pn * 256) * 2; u.R = nullptr; u.ldc = ZW; u.flag = (pn < 4) ? 1 : 0; return true; }
.LBB0_367:
	s_andn2_b64 vcc, exec, s[6:7]
	v_mov_b32_e32 v139, s8
	s_cbranch_vccnz .LBB0_373
	s_mov_b32 s100, s81
	s_bitcmp1_b32 s81, 0
	s_cbranch_scc1 .Lsw_done0
	s_cmp_lt_u32 s81, 0x80
	s_cbranch_scc0 .Lsw_done0
	s_add_i32 s81, s81, 0x180
.Lsw_done0:
	s_ashr_i32 s0, s81, 31
	s_lshr_b32 s0, s0, 29
	s_add_i32 s2, s81, s0
	s_and_b32 s0, s2, -8
	s_sub_i32 s3, s81, s0
	s_mov_b32 s81, s100
	s_cmp_gt_i32 s3, -1
	s_mov_b64 s[0:1], -1
	s_cbranch_scc0 .LBB0_370
	s_lshl_b32 s6, s3, 6
	s_mov_b64 s[0:1], 0

;     __device__ __forceinline__ bool next(int i, pg8::Unit& u) const {
;         const int L = i * G + c;
;         if (kind == 0) {
;             if (L < 512) { int pm, pn; order(L, 512, 32, 16, pm, pn);
;                 u.A = A0 + (size_t)pm * 256 * DM * 2; u.B = B0 + (size_t)pn * 256 * DM * 2; u.O = O0 + ((size_t)pm * 256 * ZW + pn * 256) * 2; u.R = nullptr; u.ldc = ZW; u.flag = (pn < 4) ? 1 : 0; return true; }
;             const int L1 = L - 512; if (L1 >= 128) return false;
;             int pm, pn; order(L1, 128, 4, 32, pm, pn);
;             u.A = A1 + (size_t)pm * 256 * DM * 2; u.B = B1 + (size_t)pn * 256 * DM * 2;
;             u.O = O1 + ((size_t)(pn >> 4) * 512 * 8192 + (size_t)(pm & 1) * 256 * 8192 + (size_t)(pm >> 1) * 4096 + (size_t)(pn & 15) * 256) * 2;
;             u.R = nullptr; u.ldc = 8192; u.flag = 0; return true;
;         } else if (kind == 2) {
;             if (L >= 128) return false;
;             const int xcd = L & 7, j = L >> 3, ks = xcd & 3, pm = (xcd >> 2) * 4 + (j & 3), pn = j >> 2;
;             u.A = A0 + ((size_t)pm * 256 * 8192 + (size_t)ks * 2048) * 2; u.B = B0 + ((size_t)pn * 256 * 8192 + (size_t)ks * 2048) * 2;
;             u.O = O0 + ((((size_t)ks * 2 + (pn >> 1)) * 2048 + (size_t)pm * 256) * 512 + (size_t)(pn & 1) * 256) * 2; u.R = nullptr; u.ldc = 512; u.flag = 0; return true;
;         } else if (kind == 3) {
;             if (L >= nM * nN) return false;
;             int pm, pn; order(L, nM * nN, nM, nN, pm, pn);
;             u.A = A0 + (size_t)pm * 256 * K * 2; u.B = B0 + (size_t)pn * 256 * K * 2; u.O = O0 + ((size_t)pm * 256 * DM + pn * 256) * 2; u.R = (const float*)((const char*)R0 + ((size_t)pm * 256 * DM + pn * 256) * (r32 ? 4 : 2)); u.ldc = DM; u.flag = r32; return true;
;         } else if (kind == 5) {
;             if (L >= 34 * 44) return false;
;             int pm, pn; order(L, 34 * 44, 34, 44, pm, pn);
;             const int b = pm / 17, j = pm % 17; const long row0 = (long)b * SEQ + 254 * j - 1;
;             u.A = A0 + row0 * DM * 2; u.B = B0 + (size_t)pn * 128 * DM * 2; u.O = O0 + (row0 * DFF + pn * 128) * 2; u.R = R0 + pn * 128; u.ldc = DFF; u.flag = j; return true;
.LBB0_380:
	s_add_i32 s63, s20, 1
	v_readlane_b32 s0, v254, 32
	s_mul_i32 s38, s63, s0
	s_add_i32 s38, s38, s81
	s_cmp_lg_u32 s50, 0
	s_cbranch_scc1 .Lsw_done1
	s_bitcmp1_b32 s38, 0
	s_cbranch_scc1 .Lsw_done1
	s_sub_i32 s100, s38, 0x180
	s_cmp_lt_u32 s100, 0x80
	s_cbranch_scc0 .Lsw_done1
	s_add_i32 s38, s38, 0xfffffe80
.Lsw_done1:
	s_cmp_lt_i32 s50, 3
	s_mov_b64 s[0:1], 0
	s_cbranch_scc1 .LBB0_386
	s_cmp_gt_i32 s50, 4
	s_cbranch_scc0 .LBB0_387
	s_cmp_eq_u32 s50, 5
	s_cbranch_scc0 .LBB0_388
	s_mov_b64 s[6:7], 0
	s_cmpk_gt_i32 s38, 0x5d7
	s_mov_b64 s[16:17], 0
	s_mov_b64 s[2:3], s[68:69]
	s_mov_b64 s[18:19], s[12:13]
	s_mov_b64 s[8:9], s[56:57]
	s_mov_b32 s26, s62
	v_mov_b32_e32 v144, v150
	s_cbranch_scc1 .LBB0_385
	s_ashr_i32 s2, s38, 31
	s_lshr_b32 s2, s2, 29
	s_add_i32 s2, s38, s2
	s_and_b32 s3, s2, -8
	s_sub_i32 s3, s38, s3
	s_cmp_lt_i32 s3, 0
	s_movk_i32 s8, 0xbc
	s_cselect_b32 s8, s8, 0xbb
	v_mov_b32_e32 v144, s3
	v_mul_i32_i24_e32 v144, s8, v144
	s_ashr_i32 s2, s2, 3
	v_readfirstlane_b32 s3, v144
	s_add_i32 s3, s3, s2
	s_mul_hi_i32 s2, s3, 0x2e8ba2e9
	s_lshr_b32 s8, s2, 31
	s_ashr_i32 s2, s2, 6
	s_add_i32 s2, s2, s8
	s_lshl_b32 s9, s2, 3
	v_mov_b32_e32 v144, 0x160
	s_sub_i32 s8, 34, s9
	v_mul_i32_i24_e32 v144, s2, v144
	s_min_u32 s16, s8, 8
	v_readfirstlane_b32 s2, v144
	s_sub_i32 s17, s3, s2
	v_cvt_f32_ubyte0_e32 v145, s16
	v_cvt_f32_i32_e32 v144, s17
	v_rcp_iflag_f32_e32 v146, v145
	s_ashr_i32 s2, s17, 30
	s_or_b32 s8, s2, 1
	s_movk_i32 s26, 0x1600
	v_mul_f32_e32 v146, v144, v146
	v_trunc_f32_e32 v146, v146
	v_fma_f32 v144, -v146, v145, v144
	v_cvt_i32_f32_e32 v146, v146
	v_cmp_ge_f32_e64 s[2:3], |v144|, v145
	s_and_b64 s[2:3], s[2:3], exec
	s_cselect_b32 s2, s8, 0
	v_readfirstlane_b32 s3, v146
	s_add_i32 s8, s3, s2
	s_mul_i32 s2, s8, s16
	s_sub_i32 s2, s17, s2
	s_sext_i32_i16 s2, s2
	s_add_i32 s9, s9, s2
	s_mul_hi_i32 s2, s9, 0x78787879
	s_lshr_b32 s3, s2, 31
	s_ashr_i32 s2, s2, 3
	s_add_i32 s2, s2, s3
	s_mul_i32 s3, s2, 17
	s_sub_i32 s36, s9, s3
	s_mul_i32 s9, s36, 0xfe
	s_ashr_i32 s3, s2, 31
	s_add_i32 s9, s9, -1
	s_lshl_b64 s[2:3], s[2:3], 12
	s_ashr_i32 s17, s9, 31
	s_add_u32 s16, s2, s9
	s_addc_u32 s17, s3, s17
	s_lshl_b64 s[2:3], s[16:17], 12
	s_add_u32 s2, s46, s2
	s_sext_i32_i16 s27, s8
	s_addc_u32 s3, s47, s3
	s_bfe_i64 s[8:9], s[8:9], 0x100000
	s_lshl_b64 s[8:9], s[8:9], 19
	s_add_u32 s18, s42, s8
	s_addc_u32 s19, s43, s9
	s_mul_i32 s8, s17, 0x1600
	s_mul_hi_u32 s9, s16, 0x1600
	s_add_i32 s9, s9, s8
	s_mul_i32 s8, s16, 0x1600
	s_lshl_b32 s16, s27, 7
	s_ashr_i32 s17, s16, 31
	s_add_u32 s8, s8, s16
	s_addc_u32 s9, s9, s17
	s_lshl_b64 s[8:9], s[8:9], 1
	s_add_u32 s8, s44, s8
	v_readlane_b32 s27, v254, 52
	s_addc_u32 s9, s45, s9
	s_mov_b64 s[16:17], -1
	v_mov_b32_e32 v144, s36
